# LRU backward pass: the 32 h_fwd/gelu(y) 2-byte loads issued at the top of the chunk iteration, converts wait vmcnt(8) only (waitcnt placement), on top of v30
# speedup vs baseline: 1.0039x; 1.0039x over previous
; __device__ __forceinline__ float bf2f(bf16_t h) { return __uint_as_float((unsigned)h << 16); }
; __device__ __forceinline__ void phase_lru(const Params& p, LAS unsigned char* lds) {
;     ...
;                 if (d == 1) {
;                     const bf16_t* const hfi = HF + (size_t)(row0 + t0 + 4 * g) * D + ch; const bf16_t* const gyi = GY + (size_t)(row0 + t0 + 4 * g) * D + ch;
; #pragma unroll
;                     for (int mt = 0; mt < 4; ++mt)
; #pragma unroll
;                         for (int j = 0; j < 4; ++j) { hfv[mt][j] = bf2f(hfi[(16 * mt + j) * D]); gyv[mt][j] = bf2f(gyi[(16 * mt + j) * D]); }
.LBB0_574:
	s_waitcnt vmcnt(0)
	s_andn2_b64 vcc, exec, s[50:51]
	s_cbranch_vccnz .Llru_e_skip
	s_add_i32 s33, s10, -1
	s_and_b64 s[8:9], s[52:53], exec
	s_cselect_b32 s8, s33, s88
	v_lshl_add_u32 v2, s8, 6, v196
	v_ashrrev_i32_e32 v3, 31, v2
	v_lshlrev_b64 v[2:3], 10, v[2:3]
	v_lshlrev_b64 v[108:109], 1, v[2:3]
	v_lshl_add_u64 v[110:111], v[122:123], 0, v[108:109]
	v_add_co_u32_e32 v112, vcc, 0x1000, v110
	v_lshl_add_u64 v[108:109], v[124:125], 0, v[108:109]
	s_nop 1
	v_addc_co_u32_e32 v113, vcc, 0, v111, vcc
	v_add_co_u32_e32 v114, vcc, 0x1000, v108
	s_nop 1
	v_addc_co_u32_e32 v115, vcc, 0, v109, vcc
	global_load_ushort v163, v[110:111], off offset:2048
	global_load_ushort v132, v[108:109], off offset:2048
	global_load_ushort v133, v[112:113], off offset:2048
	global_load_ushort v134, v[114:115], off offset:2048
	global_load_ushort v135, v[114:115], off
	global_load_ushort v138, v[112:113], off
	global_load_ushort v136, v[108:109], off
	global_load_ushort v137, v[110:111], off
	v_add_co_u32_e32 v112, vcc, 0x8000, v110
	s_nop 1
	v_addc_co_u32_e32 v113, vcc, 0, v111, vcc
	v_add_co_u32_e32 v114, vcc, 0x8000, v108
	s_nop 1
	v_addc_co_u32_e32 v115, vcc, 0, v109, vcc
	v_add_co_u32_e32 v126, vcc, 0x9000, v110
	s_nop 1
	v_addc_co_u32_e32 v127, vcc, 0, v111, vcc
	v_add_co_u32_e32 v130, vcc, 0x9000, v108
	s_nop 1
	v_addc_co_u32_e32 v131, vcc, 0, v109, vcc
	global_load_ushort v139, v[112:113], off offset:2048
	global_load_ushort v142, v[114:115], off offset:2048
	global_load_ushort v143, v[126:127], off offset:2048
	global_load_ushort v146, v[130:131], off offset:2048
	global_load_ushort v147, v[130:131], off
	global_load_ushort v148, v[126:127], off
	global_load_ushort v144, v[114:115], off
	global_load_ushort v145, v[112:113], off
	v_add_co_u32_e32 v112, vcc, 0x10000, v110
	s_nop 1
	v_addc_co_u32_e32 v113, vcc, 0, v111, vcc
	v_add_co_u32_e32 v114, vcc, 0x10000, v108
	s_nop 1
	v_addc_co_u32_e32 v115, vcc, 0, v109, vcc
	v_add_co_u32_e32 v126, vcc, 0x11000, v110
	s_nop 1
	v_addc_co_u32_e32 v127, vcc, 0, v111, vcc
	v_add_co_u32_e32 v130, vcc, 0x11000, v108
	s_nop 1
	v_addc_co_u32_e32 v131, vcc, 0, v109, vcc
	global_load_ushort v150, v[112:113], off offset:2048
	global_load_ushort v151, v[114:115], off offset:2048
	global_load_ushort v154, v[126:127], off offset:2048
	global_load_ushort v156, v[130:131], off offset:2048
	global_load_ushort v155, v[130:131], off
	global_load_ushort v157, v[126:127], off
	global_load_ushort v152, v[114:115], off
	global_load_ushort v153, v[112:113], off
	v_add_co_u32_e32 v112, vcc, 0x18000, v110
	s_nop 1
	v_addc_co_u32_e32 v113, vcc, 0, v111, vcc
	v_add_co_u32_e32 v114, vcc, 0x18000, v108
	s_nop 1
	v_addc_co_u32_e32 v115, vcc, 0, v109, vcc
	v_add_co_u32_e32 v110, vcc, 0x19000, v110
	s_nop 1
	v_addc_co_u32_e32 v111, vcc, 0, v111, vcc
	v_add_co_u32_e32 v108, vcc, 0x19000, v108
	s_nop 1
	v_addc_co_u32_e32 v109, vcc, 0, v109, vcc
	global_load_ushort v158, v[108:109], off
	global_load_ushort v159, v[110:111], off
	global_load_ushort v161, v[114:115], off
	global_load_ushort v162, v[112:113], off
	global_load_ushort v174, v[112:113], off offset:2048
	global_load_ushort v175, v[114:115], off offset:2048
	global_load_ushort v165, v[110:111], off offset:2048
	global_load_ushort v164, v[108:109], off offset:2048
; #define LAS __attribute__((address_space(3)))
; __device__ __forceinline__ unsigned pk_bf16(float lo, float hi) { const f32x2 v = {lo, hi}; const bf16x2_t b = __builtin_convertvector(v, bf16x2_t); return __builtin_bit_cast(unsigned, b); }
; __device__ __forceinline__ float lo_bf(unsigned w) { return __uint_as_float(w << 16); }
; __device__ __forceinline__ float hi_bf(unsigned w) { return __uint_as_float(w & 0xffff0000u); }
; #define LRU_PREFETCH(CI) do { const int _cc = d ? (nch - 1 - (CI)) : (CI); _Pragma("unroll") for (int hf = 0; hf < 2; ++hf) _Pragma("unroll") for (int j = 0; j < 4; ++j) { \
;                 const int tt = _cc * 64 + tr + 32 * hf + j - 1; pw[hf][j] = (tt >= 0 && tt < S) ? *(const u32x4*)(XL + (size_t)(row0 + tt) * D + c0) : (u32x4){0u, 0u, 0u, 0u}; } } while (0)
; __device__ __forceinline__ void phase_lru(const Params& p, LAS unsigned char* lds) {
;     ...
;                 __syncthreads();
; #pragma unroll
;                 for (int hf = 0; hf < 2; ++hf) {
;                     const int tl = tr + 32 * hf;
;                     float a[8];
; #pragma unroll
;                     for (int e = 0; e < 8; ++e) a[e] = cb[e];
; #pragma unroll
;                     for (int j = 0; j < 4; ++j) { const u32x4 w = pw[hf][j];
;                         a[0] += cw[j][0] * lo_bf(w.x); a[1] += cw[j][1] * hi_bf(w.x); a[2] += cw[j][2] * lo_bf(w.y); a[3] += cw[j][3] * hi_bf(w.y);
;                         a[4] += cw[j][4] * lo_bf(w.z); a[5] += cw[j][5] * hi_bf(w.z); a[6] += cw[j][6] * lo_bf(w.w); a[7] += cw[j][7] * hi_bf(w.w); }
;                     u32x4 o; o.x = pk_bf16(a[0], a[1]); o.y = pk_bf16(a[2], a[3]); o.z = pk_bf16(a[4], a[5]); o.w = pk_bf16(a[6], a[7]);
;                     *(LAS u32x4*)(lds + tl * XC_PITCH + cgp * 2) = o;
;                 }
;                 __syncthreads();
;                 if (ci + 1 < nch) LRU_PREFETCH(ci + 1);
.Llru_e_skip:
	v_lshlrev_b32_e32 v2, 16, v76
	v_and_b32_e32 v3, 0xffff0000, v76
	v_pk_fma_f32 v[2:3], v[28:29], v[2:3], v[32:33]
	v_lshlrev_b32_e32 v108, 16, v80
	v_and_b32_e32 v109, 0xffff0000, v80
	v_pk_fma_f32 v[2:3], v[4:5], v[108:109], v[2:3]
	v_lshlrev_b32_e32 v108, 16, v84
	v_and_b32_e32 v109, 0xffff0000, v84
	v_pk_fma_f32 v[2:3], v[8:9], v[108:109], v[2:3]
	v_lshlrev_b32_e32 v108, 16, v88
	v_and_b32_e32 v109, 0xffff0000, v88
	v_pk_fma_f32 v[2:3], v[20:21], v[108:109], v[2:3]
	v_lshlrev_b32_e32 v108, 16, v77
	v_and_b32_e32 v109, 0xffff0000, v77
	v_pk_fma_f32 v[108:109], v[30:31], v[108:109], v[34:35]
	v_lshlrev_b32_e32 v110, 16, v81
	v_and_b32_e32 v111, 0xffff0000, v81
	v_pk_fma_f32 v[108:109], v[6:7], v[110:111], v[108:109]
	v_lshlrev_b32_e32 v110, 16, v85
	v_and_b32_e32 v111, 0xffff0000, v85
	v_pk_fma_f32 v[108:109], v[10:11], v[110:111], v[108:109]
	v_lshlrev_b32_e32 v110, 16, v89
	v_and_b32_e32 v111, 0xffff0000, v89
	v_pk_fma_f32 v[110:111], v[22:23], v[110:111], v[108:109]
	v_lshlrev_b32_e32 v108, 16, v78
	v_and_b32_e32 v109, 0xffff0000, v78
	v_pk_fma_f32 v[108:109], v[36:37], v[108:109], v[40:41]
	v_lshlrev_b32_e32 v112, 16, v82
	v_and_b32_e32 v113, 0xffff0000, v82
	v_pk_fma_f32 v[108:109], v[12:13], v[112:113], v[108:109]
	v_lshlrev_b32_e32 v112, 16, v86
	v_and_b32_e32 v113, 0xffff0000, v86
	v_pk_fma_f32 v[108:109], v[16:17], v[112:113], v[108:109]
	v_lshlrev_b32_e32 v112, 16, v90
	v_and_b32_e32 v113, 0xffff0000, v90
	v_pk_fma_f32 v[112:113], v[24:25], v[112:113], v[108:109]
	v_lshlrev_b32_e32 v108, 16, v79
	v_and_b32_e32 v109, 0xffff0000, v79
	v_pk_fma_f32 v[108:109], v[38:39], v[108:109], v[42:43]
	v_lshlrev_b32_e32 v114, 16, v83
	v_and_b32_e32 v115, 0xffff0000, v83
	v_pk_fma_f32 v[108:109], v[14:15], v[114:115], v[108:109]
	v_lshlrev_b32_e32 v114, 16, v87
	v_and_b32_e32 v115, 0xffff0000, v87
	v_pk_fma_f32 v[108:109], v[18:19], v[114:115], v[108:109]
	v_lshlrev_b32_e32 v114, 16, v91
	v_and_b32_e32 v115, 0xffff0000, v91
	v_pk_fma_f32 v[114:115], v[26:27], v[114:115], v[108:109]
	v_cvt_pk_bf16_f32 v108, v2, v3
	v_cvt_pk_bf16_f32 v109, v110, v111
	v_cvt_pk_bf16_f32 v110, v112, v113
	v_cvt_pk_bf16_f32 v111, v114, v115
	v_lshlrev_b32_e32 v2, 16, v92
	v_and_b32_e32 v3, 0xffff0000, v92
	s_barrier
	ds_write_b128 v191, v[108:111]
	v_pk_fma_f32 v[2:3], v[28:29], v[2:3], v[32:33]
	v_lshlrev_b32_e32 v108, 16, v96
	v_and_b32_e32 v109, 0xffff0000, v96
	v_pk_fma_f32 v[2:3], v[4:5], v[108:109], v[2:3]
	v_lshlrev_b32_e32 v108, 16, v100
	v_and_b32_e32 v109, 0xffff0000, v100
	v_pk_fma_f32 v[2:3], v[8:9], v[108:109], v[2:3]
	v_lshlrev_b32_e32 v108, 16, v104
	v_and_b32_e32 v109, 0xffff0000, v104
	v_pk_fma_f32 v[2:3], v[20:21], v[108:109], v[2:3]
	v_lshlrev_b32_e32 v108, 16, v93
	v_and_b32_e32 v109, 0xffff0000, v93
	v_pk_fma_f32 v[108:109], v[30:31], v[108:109], v[34:35]
	v_lshlrev_b32_e32 v110, 16, v97
	v_and_b32_e32 v111, 0xffff0000, v97
	v_pk_fma_f32 v[108:109], v[6:7], v[110:111], v[108:109]
	v_lshlrev_b32_e32 v110, 16, v101
	v_and_b32_e32 v111, 0xffff0000, v101
	v_pk_fma_f32 v[108:109], v[10:11], v[110:111], v[108:109]
	v_lshlrev_b32_e32 v110, 16, v105
	v_and_b32_e32 v111, 0xffff0000, v105
	v_pk_fma_f32 v[110:111], v[22:23], v[110:111], v[108:109]
	v_lshlrev_b32_e32 v108, 16, v94
	v_and_b32_e32 v109, 0xffff0000, v94
	v_pk_fma_f32 v[108:109], v[36:37], v[108:109], v[40:41]
	v_lshlrev_b32_e32 v112, 16, v98
	v_and_b32_e32 v113, 0xffff0000, v98
	v_pk_fma_f32 v[108:109], v[12:13], v[112:113], v[108:109]
	v_lshlrev_b32_e32 v112, 16, v102
	v_and_b32_e32 v113, 0xffff0000, v102
	v_pk_fma_f32 v[108:109], v[16:17], v[112:113], v[108:109]
	v_lshlrev_b32_e32 v112, 16, v106
	v_and_b32_e32 v113, 0xffff0000, v106
	v_pk_fma_f32 v[112:113], v[24:25], v[112:113], v[108:109]
	v_lshlrev_b32_e32 v108, 16, v95
	v_and_b32_e32 v109, 0xffff0000, v95
	v_pk_fma_f32 v[108:109], v[38:39], v[108:109], v[42:43]
	v_lshlrev_b32_e32 v114, 16, v99
	v_and_b32_e32 v115, 0xffff0000, v99
	v_pk_fma_f32 v[108:109], v[14:15], v[114:115], v[108:109]
	v_lshlrev_b32_e32 v114, 16, v103
	v_and_b32_e32 v115, 0xffff0000, v103
	v_pk_fma_f32 v[108:109], v[18:19], v[114:115], v[108:109]
	v_lshlrev_b32_e32 v114, 16, v107
	v_and_b32_e32 v115, 0xffff0000, v107
	v_pk_fma_f32 v[114:115], v[26:27], v[114:115], v[108:109]
	v_cvt_pk_bf16_f32 v108, v2, v3
	v_cvt_pk_bf16_f32 v109, v110, v111
	v_cvt_pk_bf16_f32 v110, v112, v113
	v_cvt_pk_bf16_f32 v111, v114, v115
	s_cmp_ge_u32 s10, s79
	ds_write_b128 v191, v[108:111] offset:8704
	s_waitcnt lgkmcnt(0)
	s_barrier
	s_cbranch_scc1 .Llru_e_w0
	s_add_i32 s33, s88, -1
	s_and_b64 s[8:9], s[52:53], exec
	s_cselect_b32 s33, s10, s33
	s_cmp_lt_i32 s33, 1
	s_cbranch_scc1 .Llru_pf_slow
	s_lshr_b32 s32, s78, 6
	s_add_i32 s32, s32, -1
	s_cmp_ge_i32 s33, s32
	s_cbranch_scc1 .Llru_pf_slow
	v_lshl_or_b32 v1, s33, 6, v184
	v_add_u32_e32 v2, s77, v1
	v_add_u32_e32 v2, 1, v2
	v_ashrrev_i32_e32 v3, 31, v2
	v_lshlrev_b64 v[2:3], 11, v[2:3]
	v_lshl_add_u64 v[2:3], v[120:121], 0, v[2:3]
	s_mov_b64 s[68:69], 0x10000
	v_lshl_add_u64 v[108:109], v[2:3], 0, s[68:69]
	global_load_dwordx4 v[76:79], v[2:3], off offset:-4096
	global_load_dwordx4 v[80:83], v[2:3], off offset:-2048
	global_load_dwordx4 v[84:87], v[2:3], off
	global_load_dwordx4 v[88:91], v[2:3], off offset:2048
	global_load_dwordx4 v[92:95], v[108:109], off offset:-4096
	global_load_dwordx4 v[96:99], v[108:109], off offset:-2048
	global_load_dwordx4 v[100:103], v[108:109], off
	global_load_dwordx4 v[104:107], v[108:109], off offset:2048
	s_branch .LBB0_592

; __device__ __forceinline__ float bf2f(bf16_t h) { return __uint_as_float((unsigned)h << 16); }
; __device__ __forceinline__ void phase_lru(const Params& p, LAS unsigned char* lds) {
;     ...
;                 if (d == 1) {
;                     const bf16_t* const hfi = HF + (size_t)(row0 + t0 + 4 * g) * D + ch; const bf16_t* const gyi = GY + (size_t)(row0 + t0 + 4 * g) * D + ch;
; #pragma unroll
;                     for (int mt = 0; mt < 4; ++mt)
; #pragma unroll
;                         for (int j = 0; j < 4; ++j) { hfv[mt][j] = bf2f(hfi[(16 * mt + j) * D]); gyv[mt][j] = bf2f(gyi[(16 * mt + j) * D]); }
.LBB0_591:
	s_or_b64 exec, exec, s[8:9]
.Llru_e_w0:
	s_waitcnt vmcnt(0)
.LBB0_592:
	s_add_i32 s33, s10, -1
	s_and_b64 s[8:9], s[52:53], exec
	s_cselect_b32 s8, s33, s88
	v_lshl_add_u32 v2, s8, 6, v196
	v_ashrrev_i32_e32 v3, 31, v2
	s_andn2_b64 vcc, exec, s[50:51]
	v_lshlrev_b64 v[2:3], 10, v[2:3]
	s_cbranch_vccnz .LBB0_594
	s_waitcnt vmcnt(8)
	v_lshlrev_b32_e32 v140, 16, v134
	v_lshlrev_b32_e32 v141, 16, v135
	v_lshlrev_b32_e32 v134, 16, v143
	v_lshlrev_b32_e32 v135, 16, v148
	v_lshlrev_b32_e32 v149, 16, v147
	v_lshlrev_b32_e32 v148, 16, v146
	v_lshlrev_b32_e32 v127, 16, v137
	v_lshlrev_b32_e32 v126, 16, v163
	v_lshlrev_b32_e32 v137, 16, v136
	v_lshlrev_b32_e32 v136, 16, v132
	v_lshlrev_b32_e32 v131, 16, v138
	v_lshlrev_b32_e32 v130, 16, v133
	v_lshlrev_b32_e32 v133, 16, v145
	v_lshlrev_b32_e32 v132, 16, v139
	v_lshlrev_b32_e32 v145, 16, v144
	v_lshlrev_b32_e32 v144, 16, v142
	v_lshlrev_b32_e32 v138, 16, v150
	v_lshlrev_b32_e32 v142, 16, v154
	v_lshlrev_b32_e32 v154, 16, v156
	v_lshlrev_b32_e32 v155, 16, v155
	v_lshlrev_b32_e32 v143, 16, v157
	v_lshlrev_b32_e32 v139, 16, v153
	v_lshlrev_b32_e32 v153, 16, v152
	v_lshlrev_b32_e32 v152, 16, v151
	v_lshlrev_b32_e32 v151, 16, v159
	v_lshlrev_b32_e32 v157, 16, v161
	v_lshlrev_b32_e32 v147, 16, v162
	v_lshlrev_b32_e32 v146, 16, v174
	v_lshlrev_b32_e32 v156, 16, v175
	v_lshlrev_b32_e32 v150, 16, v165
	v_lshlrev_b32_e32 v159, 16, v158
	v_lshlrev_b32_e32 v158, 16, v164
